# v63 + merged GEMM (P4): per-unit epilogue alignment rendezvous dropped (wave halves stay staggered across the a/b/c units), final compensation barrier kept
# speedup vs baseline: 1.0025x; 1.0025x over previous
; #define PG8_STAGE(bufoff, gbase, voff) do { _Pragma("unroll") for (int _i = 0; _i < 2; ++_i) \
;         __builtin_amdgcn_global_load_lds((const GAS unsigned*)((const GAS char*)(gbase) + (voff)[_i]), (LAS unsigned*)(lds + (bufoff) + ldsw + _i * 8192), 16, 0, 0); } while (0)
; #define PG8_LDA(dst, b, h) do { _Pragma("unroll") for (int m = 0; m < 4; ++m) _Pragma("unroll") for (int k = 0; k < 2; ++k) dst[m][k] = *(const LAS bf16x8*)(lds + PG8_SA(b, h) + aoff + m * 2048 + k * 1024); } while (0)
; #define PG8_LDB(dst, b, h) do { _Pragma("unroll") for (int n = 0; n < 2; ++n) _Pragma("unroll") for (int k = 0; k < 2; ++k) dst[n][k] = *(const LAS bf16x8*)(lds + PG8_SB(b, h) + boff + n * 2048 + k * 1024); } while (0)
; #define PG8_MMA(ai, bj, At, Bt) do { __builtin_amdgcn_sched_barrier(0); _Pragma("unroll") for (int m = 0; m < 4; ++m) _Pragma("unroll") for (int n = 0; n < 2; ++n) _Pragma("unroll") for (int k = 0; k < 2; ++k) \
;         acc[ai][bj][m][n] = __builtin_amdgcn_mfma_f32_16x16x32_bf16(Bt[n][k], At[m][k], acc[ai][bj][m][n], 0, 0, 0); __builtin_amdgcn_sched_barrier(0); } while (0)
; #define PG8_WAIT_V(n) asm volatile("s_waitcnt vmcnt(" #n ")" ::: "memory")
; #define PG8_WAIT_L(n) asm volatile("s_waitcnt lgkmcnt(" #n ")" ::: "memory")
; #define PG8_BAR __builtin_amdgcn_s_barrier()
; #define PG8_SCHED __builtin_amdgcn_sched_barrier(0)
; template <class Epi, class Sched, bool ALIGN_EPI, bool SP2>
; __device__ __forceinline__ void gemm_phase(LAS unsigned char* lds, const int tid, const Gemm g, const Sched& S, const Epi& E) {
;     ...
;             PG8_LDB(B0, 0, 0); PG8_LDB(B1, 0, 1); PG8_SCHED; PG8_LDA(At, 0, 0); PG8_STAGE(PG8_SA(1, 1), a1 + hstepA, voffA);
;             PG8_WAIT_V(8); PG8_WAIT_L(0); PG8_BAR; PG8_MMA(0, 0, At, B0); PG8_MMA(0, 1, At, B1); PG8_BAR; PG8_SCHED;
;             PG8_LDA(At, 0, 1); PG8_STAGE(PG8_SB(0, 0), b2, voffB); PG8_STAGE(PG8_SB(0, 1), b2 + hstepB, voffB); PG8_STAGE(PG8_SA(0, 0), a2, voffA);
;             PG8_WAIT_V(8); PG8_WAIT_L(0); PG8_BAR; PG8_MMA(1, 0, At, B0); PG8_MMA(1, 1, At, B1); PG8_BAR; PG8_SCHED;
.LBB0_1128:
	s_add_i32 s61, s26, 2
	s_add_u32 s27, s24, 0xfff80080
	s_addc_u32 s42, s25, -1
	s_add_i32 s70, 0, 0x10000
	s_cmp_eq_u32 s7, s26
	s_cselect_b32 s43, s35, s42
	s_cselect_b32 s42, s34, s27
	s_cselect_b32 s27, s55, s53
	s_cselect_b32 s26, s54, s11
	s_add_i32 s82, 0, 0x14000
	v_add_u32_e32 v142, s70, v207
	v_add_u32_e32 v158, s82, v207
	ds_read_b128 v[130:133], v142
	ds_read_b128 v[134:137], v142 offset:1024
	ds_read_b128 v[138:141], v142 offset:2048
	ds_read_b128 v[142:145], v142 offset:3072
	ds_read_b128 v[146:149], v158
	ds_read_b128 v[150:153], v158 offset:1024
	ds_read_b128 v[154:157], v158 offset:2048
	ds_read_b128 v[158:161], v158 offset:3072
	v_lshl_add_u64 v[216:217], s[24:25], 0, v[214:215]
	s_add_i32 m0, s19, 0xc000
	ds_read_b128 v[162:165], v247
	ds_read_b128 v[166:169], v247 offset:1024
	ds_read_b128 v[170:173], v247 offset:2048
	ds_read_b128 v[174:177], v247 offset:3072
	ds_read_b128 v[178:181], v247 offset:4096
	ds_read_b128 v[182:185], v247 offset:5120
	ds_read_b128 v[186:189], v247 offset:6144
	ds_read_b128 v[190:193], v247 offset:7168
	global_load_lds_dwordx4 v[216:217], off
	v_lshl_add_u64 v[216:217], s[24:25], 0, v[200:201]
	s_add_i32 m0, s19, 0xe000
	s_nop 0
	global_load_lds_dwordx4 v[216:217], off
	s_waitcnt vmcnt(8)
	s_waitcnt lgkmcnt(0)
	s_barrier
	s_waitcnt lgkmcnt(0)
	v_mfma_f32_16x16x32_bf16 v[126:129], v[130:133], v[162:165], v[126:129]
	v_mfma_f32_16x16x32_bf16 v[122:125], v[138:141], v[162:165], v[122:125]
	v_mfma_f32_16x16x32_bf16 v[118:121], v[130:133], v[170:173], v[118:121]
	v_mfma_f32_16x16x32_bf16 v[114:117], v[138:141], v[170:173], v[114:117]
	v_mfma_f32_16x16x32_bf16 v[110:113], v[130:133], v[178:181], v[110:113]
	v_mfma_f32_16x16x32_bf16 v[106:109], v[138:141], v[178:181], v[106:109]
	v_mfma_f32_16x16x32_bf16 v[102:105], v[130:133], v[186:189], v[102:105]
	v_mfma_f32_16x16x32_bf16 v[98:101], v[138:141], v[186:189], v[98:101]
	v_mfma_f32_16x16x32_bf16 v[126:129], v[134:137], v[166:169], v[126:129]
	v_mfma_f32_16x16x32_bf16 v[122:125], v[142:145], v[166:169], v[122:125]
	v_mfma_f32_16x16x32_bf16 v[118:121], v[134:137], v[174:177], v[118:121]
	v_mfma_f32_16x16x32_bf16 v[114:117], v[142:145], v[174:177], v[114:117]
	v_mfma_f32_16x16x32_bf16 v[110:113], v[134:137], v[182:185], v[110:113]
	v_mfma_f32_16x16x32_bf16 v[106:109], v[142:145], v[182:185], v[106:109]
	v_mfma_f32_16x16x32_bf16 v[102:105], v[134:137], v[190:193], v[102:105]
	v_mfma_f32_16x16x32_bf16 v[98:101], v[142:145], v[190:193], v[98:101]
	v_mfma_f32_16x16x32_bf16 v[94:97], v[146:149], v[162:165], v[94:97]
	v_mfma_f32_16x16x32_bf16 v[90:93], v[154:157], v[162:165], v[90:93]
	v_mfma_f32_16x16x32_bf16 v[86:89], v[146:149], v[170:173], v[86:89]
	v_mfma_f32_16x16x32_bf16 v[82:85], v[154:157], v[170:173], v[82:85]
	v_mfma_f32_16x16x32_bf16 v[78:81], v[146:149], v[178:181], v[78:81]
	v_mfma_f32_16x16x32_bf16 v[74:77], v[154:157], v[178:181], v[74:77]
	v_mfma_f32_16x16x32_bf16 v[70:73], v[146:149], v[186:189], v[70:73]
	v_mfma_f32_16x16x32_bf16 v[66:69], v[154:157], v[186:189], v[66:69]
	v_mfma_f32_16x16x32_bf16 v[94:97], v[150:153], v[166:169], v[94:97]
	v_mfma_f32_16x16x32_bf16 v[90:93], v[158:161], v[166:169], v[90:93]
	v_mfma_f32_16x16x32_bf16 v[86:89], v[150:153], v[174:177], v[86:89]
	v_mfma_f32_16x16x32_bf16 v[82:85], v[158:161], v[174:177], v[82:85]
	v_mfma_f32_16x16x32_bf16 v[78:81], v[150:153], v[182:185], v[78:81]
	v_mfma_f32_16x16x32_bf16 v[74:77], v[158:161], v[182:185], v[74:77]
	v_mfma_f32_16x16x32_bf16 v[70:73], v[150:153], v[190:193], v[70:73]
	v_mfma_f32_16x16x32_bf16 v[66:69], v[158:161], v[190:193], v[66:69]
	s_barrier
	s_add_i32 s70, s70, s68
	v_lshl_add_u64 v[216:217], s[26:27], 0, v[202:203]
	s_mov_b32 m0, s70
	ds_read_b128 v[162:165], v247 offset:16384
	ds_read_b128 v[166:169], v247 offset:17408
	ds_read_b128 v[170:173], v247 offset:18432
	ds_read_b128 v[174:177], v247 offset:19456
	ds_read_b128 v[178:181], v247 offset:20480
	ds_read_b128 v[182:185], v247 offset:21504
	ds_read_b128 v[186:189], v247 offset:22528
	ds_read_b128 v[190:193], v247 offset:23552
	global_load_lds_dwordx4 v[216:217], off
	s_add_i32 m0, s70, 0x2000
	s_add_u32 s70, s26, 0x80000
	v_lshl_add_u64 v[218:219], s[26:27], 0, v[198:199]
	s_addc_u32 s71, s27, 0
	s_add_i32 s82, s82, s68
	global_load_lds_dwordx4 v[218:219], off
	v_lshl_add_u64 v[220:221], s[70:71], 0, v[202:203]
	s_mov_b32 m0, s82
	v_lshl_add_u64 v[222:223], s[42:43], 0, v[196:197]
	global_load_lds_dwordx4 v[220:221], off
	v_lshl_add_u64 v[220:221], s[70:71], 0, v[198:199]
	s_add_i32 m0, s82, 0x2000
	s_nop 0
	global_load_lds_dwordx4 v[220:221], off
	v_lshl_add_u64 v[220:221], s[42:43], 0, v[194:195]
	s_mov_b32 m0, s19
	s_nop 0
	global_load_lds_dwordx4 v[220:221], off
	s_mov_b32 m0, s69
	s_nop 0
	global_load_lds_dwordx4 v[222:223], off
	s_waitcnt vmcnt(8)
	s_waitcnt lgkmcnt(0)
	s_barrier
; #define PG8_STAGE(bufoff, gbase, voff) do { _Pragma("unroll") for (int _i = 0; _i < 2; ++_i) \
;         __builtin_amdgcn_global_load_lds((const GAS unsigned*)((const GAS char*)(gbase) + (voff)[_i]), (LAS unsigned*)(lds + (bufoff) + ldsw + _i * 8192), 16, 0, 0); } while (0)
; #define PG8_LDA(dst, b, h) do { _Pragma("unroll") for (int m = 0; m < 4; ++m) _Pragma("unroll") for (int k = 0; k < 2; ++k) dst[m][k] = *(const LAS bf16x8*)(lds + PG8_SA(b, h) + aoff + m * 2048 + k * 1024); } while (0)
; #define PG8_LDB(dst, b, h) do { _Pragma("unroll") for (int n = 0; n < 2; ++n) _Pragma("unroll") for (int k = 0; k < 2; ++k) dst[n][k] = *(const LAS bf16x8*)(lds + PG8_SB(b, h) + boff + n * 2048 + k * 1024); } while (0)
; #define PG8_MMA(ai, bj, At, Bt) do { __builtin_amdgcn_sched_barrier(0); _Pragma("unroll") for (int m = 0; m < 4; ++m) _Pragma("unroll") for (int n = 0; n < 2; ++n) _Pragma("unroll") for (int k = 0; k < 2; ++k) \
;         acc[ai][bj][m][n] = __builtin_amdgcn_mfma_f32_16x16x32_bf16(Bt[n][k], At[m][k], acc[ai][bj][m][n], 0, 0, 0); __builtin_amdgcn_sched_barrier(0); } while (0)
; #define PG8_WAIT_V(n) asm volatile("s_waitcnt vmcnt(" #n ")" ::: "memory")
; #define PG8_WAIT_L(n) asm volatile("s_waitcnt lgkmcnt(" #n ")" ::: "memory")
; #define PG8_BAR __builtin_amdgcn_s_barrier()
; #define PG8_SCHED __builtin_amdgcn_sched_barrier(0)
; template <class Epi, class Sched, bool ALIGN_EPI, bool SP2>
; __device__ __forceinline__ void gemm_phase(LAS unsigned char* lds, const int tid, const Gemm g, const Sched& S, const Epi& E) {
;     ...
;             PG8_WAIT_V(8); PG8_WAIT_L(0); PG8_BAR; PG8_MMA(1, 0, At, B0); PG8_MMA(1, 1, At, B1); PG8_BAR; PG8_SCHED;
;             PG8_LDB(B0, 1, 0); PG8_LDB(B1, 1, 1); PG8_SCHED; PG8_LDA(At, 1, 0); PG8_STAGE(PG8_SA(0, 1), a2 + hstepA, voffA);
;             PG8_WAIT_V(8); PG8_WAIT_L(0); PG8_BAR; PG8_MMA(0, 0, At, B0); PG8_MMA(0, 1, At, B1); PG8_BAR; PG8_SCHED;
;             PG8_LDA(At, 1, 1); PG8_STAGE(PG8_SB(1, 0), b3, voffB); PG8_STAGE(PG8_SB(1, 1), b3 + hstepB, voffB); PG8_STAGE(PG8_SA(1, 0), a3, voffA);
	s_waitcnt lgkmcnt(0)
	v_mfma_f32_16x16x32_bf16 v[62:65], v[130:133], v[162:165], v[62:65]
	v_mfma_f32_16x16x32_bf16 v[58:61], v[138:141], v[162:165], v[58:61]
	v_mfma_f32_16x16x32_bf16 v[54:57], v[130:133], v[170:173], v[54:57]
	v_mfma_f32_16x16x32_bf16 v[50:53], v[138:141], v[170:173], v[50:53]
	v_mfma_f32_16x16x32_bf16 v[46:49], v[130:133], v[178:181], v[46:49]
	v_mfma_f32_16x16x32_bf16 v[42:45], v[138:141], v[178:181], v[42:45]
	v_mfma_f32_16x16x32_bf16 v[38:41], v[130:133], v[186:189], v[38:41]
	v_mfma_f32_16x16x32_bf16 v[34:37], v[138:141], v[186:189], v[34:37]
	v_mfma_f32_16x16x32_bf16 v[62:65], v[134:137], v[166:169], v[62:65]
	v_mfma_f32_16x16x32_bf16 v[58:61], v[142:145], v[166:169], v[58:61]
	v_mfma_f32_16x16x32_bf16 v[54:57], v[134:137], v[174:177], v[54:57]
	v_mfma_f32_16x16x32_bf16 v[50:53], v[142:145], v[174:177], v[50:53]
	v_mfma_f32_16x16x32_bf16 v[46:49], v[134:137], v[182:185], v[46:49]
	v_mfma_f32_16x16x32_bf16 v[42:45], v[142:145], v[182:185], v[42:45]
	v_mfma_f32_16x16x32_bf16 v[38:41], v[134:137], v[190:193], v[38:41]
	v_mfma_f32_16x16x32_bf16 v[34:37], v[142:145], v[190:193], v[34:37]
	v_mfma_f32_16x16x32_bf16 v[30:33], v[146:149], v[162:165], v[30:33]
	v_mfma_f32_16x16x32_bf16 v[26:29], v[154:157], v[162:165], v[26:29]
	v_mfma_f32_16x16x32_bf16 v[22:25], v[146:149], v[170:173], v[22:25]
	v_mfma_f32_16x16x32_bf16 v[18:21], v[154:157], v[170:173], v[18:21]
	v_mfma_f32_16x16x32_bf16 v[14:17], v[146:149], v[178:181], v[14:17]
	v_mfma_f32_16x16x32_bf16 v[10:13], v[154:157], v[178:181], v[10:13]
	v_mfma_f32_16x16x32_bf16 v[6:9], v[146:149], v[186:189], v[6:9]
	v_mfma_f32_16x16x32_bf16 v[2:5], v[154:157], v[186:189], v[2:5]
	v_mfma_f32_16x16x32_bf16 v[30:33], v[150:153], v[166:169], v[30:33]
	v_mfma_f32_16x16x32_bf16 v[26:29], v[158:161], v[166:169], v[26:29]
	v_mfma_f32_16x16x32_bf16 v[22:25], v[150:153], v[174:177], v[22:25]
	v_mfma_f32_16x16x32_bf16 v[18:21], v[158:161], v[174:177], v[18:21]
	v_mfma_f32_16x16x32_bf16 v[14:17], v[150:153], v[182:185], v[14:17]
	v_mfma_f32_16x16x32_bf16 v[10:13], v[158:161], v[182:185], v[10:13]
	v_mfma_f32_16x16x32_bf16 v[6:9], v[150:153], v[190:193], v[6:9]
	v_mfma_f32_16x16x32_bf16 v[2:5], v[158:161], v[190:193], v[2:5]
	s_barrier
	s_add_i32 s70, 0, 0x18000
	s_add_i32 s71, 0, 0x1c000
	v_add_u32_e32 v142, s70, v207
	v_add_u32_e32 v158, s71, v207
	ds_read_b128 v[130:133], v142
	ds_read_b128 v[134:137], v142 offset:1024
	ds_read_b128 v[138:141], v142 offset:2048
	ds_read_b128 v[142:145], v142 offset:3072
	ds_read_b128 v[146:149], v158
	ds_read_b128 v[150:153], v158 offset:1024
	ds_read_b128 v[154:157], v158 offset:2048
	ds_read_b128 v[158:161], v158 offset:3072
	s_add_u32 s42, s42, 0x80000
	s_addc_u32 s43, s43, 0
	s_mov_b32 m0, s72
	v_lshl_add_u64 v[224:225], s[42:43], 0, v[194:195]
	ds_read_b128 v[162:165], v247 offset:32768
	ds_read_b128 v[166:169], v247 offset:33792
	ds_read_b128 v[170:173], v247 offset:34816
	ds_read_b128 v[174:177], v247 offset:35840
	ds_read_b128 v[178:181], v247 offset:36864
	ds_read_b128 v[182:185], v247 offset:37888
	ds_read_b128 v[186:189], v247 offset:38912
	ds_read_b128 v[190:193], v247 offset:39936
	global_load_lds_dwordx4 v[224:225], off
	v_lshl_add_u64 v[224:225], s[42:43], 0, v[196:197]
	s_mov_b32 m0, s73
	s_nop 0
	global_load_lds_dwordx4 v[224:225], off
	s_waitcnt vmcnt(8)
	s_waitcnt lgkmcnt(0)
	s_barrier
	s_waitcnt lgkmcnt(0)
	v_mfma_f32_16x16x32_bf16 v[126:129], v[130:133], v[162:165], v[126:129]
	v_mfma_f32_16x16x32_bf16 v[122:125], v[138:141], v[162:165], v[122:125]
	v_mfma_f32_16x16x32_bf16 v[118:121], v[130:133], v[170:173], v[118:121]
	v_mfma_f32_16x16x32_bf16 v[114:117], v[138:141], v[170:173], v[114:117]
	v_mfma_f32_16x16x32_bf16 v[110:113], v[130:133], v[178:181], v[110:113]
	v_mfma_f32_16x16x32_bf16 v[106:109], v[138:141], v[178:181], v[106:109]
	v_mfma_f32_16x16x32_bf16 v[102:105], v[130:133], v[186:189], v[102:105]
	v_mfma_f32_16x16x32_bf16 v[98:101], v[138:141], v[186:189], v[98:101]
	v_mfma_f32_16x16x32_bf16 v[126:129], v[134:137], v[166:169], v[126:129]
	v_mfma_f32_16x16x32_bf16 v[122:125], v[142:145], v[166:169], v[122:125]
	v_mfma_f32_16x16x32_bf16 v[118:121], v[134:137], v[174:177], v[118:121]
	v_mfma_f32_16x16x32_bf16 v[114:117], v[142:145], v[174:177], v[114:117]
	v_mfma_f32_16x16x32_bf16 v[110:113], v[134:137], v[182:185], v[110:113]
	v_mfma_f32_16x16x32_bf16 v[106:109], v[142:145], v[182:185], v[106:109]
	v_mfma_f32_16x16x32_bf16 v[102:105], v[134:137], v[190:193], v[102:105]
	v_mfma_f32_16x16x32_bf16 v[98:101], v[142:145], v[190:193], v[98:101]
	v_mfma_f32_16x16x32_bf16 v[94:97], v[146:149], v[162:165], v[94:97]
	v_mfma_f32_16x16x32_bf16 v[90:93], v[154:157], v[162:165], v[90:93]
	v_mfma_f32_16x16x32_bf16 v[86:89], v[146:149], v[170:173], v[86:89]
	v_mfma_f32_16x16x32_bf16 v[82:85], v[154:157], v[170:173], v[82:85]
	v_mfma_f32_16x16x32_bf16 v[78:81], v[146:149], v[178:181], v[78:81]
	v_mfma_f32_16x16x32_bf16 v[74:77], v[154:157], v[178:181], v[74:77]
	v_mfma_f32_16x16x32_bf16 v[70:73], v[146:149], v[186:189], v[70:73]
	v_mfma_f32_16x16x32_bf16 v[66:69], v[154:157], v[186:189], v[66:69]
	v_mfma_f32_16x16x32_bf16 v[94:97], v[150:153], v[166:169], v[94:97]
	v_mfma_f32_16x16x32_bf16 v[90:93], v[158:161], v[166:169], v[90:93]
	v_mfma_f32_16x16x32_bf16 v[86:89], v[150:153], v[174:177], v[86:89]
	v_mfma_f32_16x16x32_bf16 v[82:85], v[158:161], v[174:177], v[82:85]
	v_mfma_f32_16x16x32_bf16 v[78:81], v[150:153], v[182:185], v[78:81]
	v_mfma_f32_16x16x32_bf16 v[74:77], v[158:161], v[182:185], v[74:77]
	v_mfma_f32_16x16x32_bf16 v[70:73], v[150:153], v[190:193], v[70:73]
	v_mfma_f32_16x16x32_bf16 v[66:69], v[158:161], v[190:193], v[66:69]
	s_barrier
; #define PG8_STAGE(bufoff, gbase, voff) do { _Pragma("unroll") for (int _i = 0; _i < 2; ++_i) \
;         __builtin_amdgcn_global_load_lds((const GAS unsigned*)((const GAS char*)(gbase) + (voff)[_i]), (LAS unsigned*)(lds + (bufoff) + ldsw + _i * 8192), 16, 0, 0); } while (0)
; #define PG8_WAIT_V(n) asm volatile("s_waitcnt vmcnt(" #n ")" ::: "memory")
; #define PG8_BAR __builtin_amdgcn_s_barrier()
; template <class Epi, class Sched, bool ALIGN_EPI, bool SP2>
; __device__ __forceinline__ void gemm_phase(LAS unsigned char* lds, const int tid, const Gemm g, const Sched& S, const Epi& E) {
;     ...
;             PG8_LDA(At, 1, 1); PG8_STAGE(PG8_SB(1, 0), b3, voffB); PG8_STAGE(PG8_SB(1, 1), b3 + hstepB, voffB); PG8_STAGE(PG8_SA(1, 0), a3, voffA);
;             PG8_WAIT_V(8); PG8_WAIT_L(0); PG8_BAR; PG8_MMA(1, 0, At, B0); PG8_MMA(1, 1, At, B1); PG8_BAR; PG8_SCHED;
;             } else {
;             PG8_LDB(B0, 0, 0); PG8_SCHED; PG8_LDA(At, 0, 0); PG8_STAGE(PG8_SA(1, 1), a1 + hstepA, voffA);
;             PG8_WAIT_L(8); PG8_BAR; PG8_WAIT_L(0); PG8_MMA(0, 0, At, B0); PG8_BAR; PG8_SCHED;
;             PG8_LDB(B1, 0, 1); PG8_STAGE(PG8_SB(0, 0), b2, voffB);
;             PG8_BAR; PG8_WAIT_L(0); PG8_MMA(0, 1, At, B1); PG8_BAR;
;             PG8_LDA(At, 0, 1); PG8_STAGE(PG8_SA(0, 0), a2, voffA);
;             PG8_BAR; PG8_WAIT_L(0); PG8_MMA(1, 0, At, B0); PG8_BAR; PG8_SCHED;
;             PG8_STAGE(PG8_SB(0, 1), b2 + hstepB, voffB);
;             PG8_WAIT_V(6); PG8_BAR; PG8_MMA(1, 1, At, B1); PG8_BAR;
;             PG8_LDB(B0, 1, 0); PG8_SCHED; PG8_LDA(At, 1, 0); PG8_STAGE(PG8_SA(0, 1), a2 + hstepA, voffA);
;             PG8_WAIT_L(8); PG8_BAR; PG8_WAIT_L(0); PG8_MMA(0, 0, At, B0); PG8_BAR; PG8_SCHED;
;             PG8_LDB(B1, 1, 1); PG8_STAGE(PG8_SB(1, 0), b3, voffB);
;             PG8_BAR; PG8_WAIT_L(0); PG8_MMA(0, 1, At, B1); PG8_BAR;
;             PG8_LDA(At, 1, 1); PG8_STAGE(PG8_SA(1, 0), a3, voffA);
;             PG8_BAR; PG8_WAIT_L(0); PG8_MMA(1, 0, At, B0); PG8_BAR; PG8_SCHED;
;             PG8_STAGE(PG8_SB(1, 1), b3 + hstepB, voffB);
;             PG8_WAIT_V(6); PG8_BAR; PG8_MMA(1, 1, At, B1); PG8_BAR;
;             }
;         }
;         if constexpr (ALIGN_EPI) { if (wr == 0) PG8_BAR; }
;         if constexpr (Epi::FUSED_LAST) { if (has_next) E(acc, cur, wr, wc, fr, fq); }
;         else E(acc, cur, wr, wc, fr, fq);
;         if (!has_next) break;
	s_add_i32 s42, s70, s68
	v_lshl_add_u64 v[216:217], v[216:217], 0, s[14:15]
	s_mov_b32 m0, s42
	ds_read_b128 v[162:165], v247 offset:49152
	ds_read_b128 v[166:169], v247 offset:50176
	ds_read_b128 v[170:173], v247 offset:51200
	ds_read_b128 v[174:177], v247 offset:52224
	ds_read_b128 v[178:181], v247 offset:53248
	ds_read_b128 v[182:185], v247 offset:54272
	ds_read_b128 v[186:189], v247 offset:55296
	ds_read_b128 v[190:193], v247 offset:56320
	global_load_lds_dwordx4 v[216:217], off
	s_add_i32 m0, s42, 0x2000
	s_add_u32 s26, s26, 0x80080
	v_lshl_add_u64 v[216:217], v[218:219], 0, s[14:15]
	s_addc_u32 s27, s27, 0
	s_add_i32 s42, s71, s68
	global_load_lds_dwordx4 v[216:217], off
	v_lshl_add_u64 v[216:217], s[26:27], 0, v[202:203]
	s_mov_b32 m0, s42
	s_nop 0
	global_load_lds_dwordx4 v[216:217], off
	v_lshl_add_u64 v[216:217], s[26:27], 0, v[198:199]
	s_add_i32 m0, s42, 0x2000
	s_nop 0
	global_load_lds_dwordx4 v[216:217], off
	v_lshl_add_u64 v[216:217], v[220:221], 0, s[14:15]
	s_mov_b32 m0, s91
	s_nop 0
	global_load_lds_dwordx4 v[216:217], off
	v_lshl_add_u64 v[216:217], v[222:223], 0, s[14:15]
	s_mov_b32 m0, s64
	s_nop 0
	global_load_lds_dwordx4 v[216:217], off
	s_waitcnt vmcnt(8)
	s_waitcnt lgkmcnt(0)
	s_barrier
	s_waitcnt lgkmcnt(0)
	v_mfma_f32_16x16x32_bf16 v[62:65], v[130:133], v[162:165], v[62:65]
	v_mfma_f32_16x16x32_bf16 v[58:61], v[138:141], v[162:165], v[58:61]
	v_mfma_f32_16x16x32_bf16 v[54:57], v[130:133], v[170:173], v[54:57]
	v_mfma_f32_16x16x32_bf16 v[50:53], v[138:141], v[170:173], v[50:53]
	v_mfma_f32_16x16x32_bf16 v[46:49], v[130:133], v[178:181], v[46:49]
	v_mfma_f32_16x16x32_bf16 v[42:45], v[138:141], v[178:181], v[42:45]
	v_mfma_f32_16x16x32_bf16 v[38:41], v[130:133], v[186:189], v[38:41]
	v_mfma_f32_16x16x32_bf16 v[34:37], v[138:141], v[186:189], v[34:37]
	v_mfma_f32_16x16x32_bf16 v[62:65], v[134:137], v[166:169], v[62:65]
	v_mfma_f32_16x16x32_bf16 v[58:61], v[142:145], v[166:169], v[58:61]
	v_mfma_f32_16x16x32_bf16 v[54:57], v[134:137], v[174:177], v[54:57]
	v_mfma_f32_16x16x32_bf16 v[50:53], v[142:145], v[174:177], v[50:53]
	v_mfma_f32_16x16x32_bf16 v[46:49], v[134:137], v[182:185], v[46:49]
	v_mfma_f32_16x16x32_bf16 v[42:45], v[142:145], v[182:185], v[42:45]
	v_mfma_f32_16x16x32_bf16 v[38:41], v[134:137], v[190:193], v[38:41]
	v_mfma_f32_16x16x32_bf16 v[34:37], v[142:145], v[190:193], v[34:37]
	v_mfma_f32_16x16x32_bf16 v[30:33], v[146:149], v[162:165], v[30:33]
	v_mfma_f32_16x16x32_bf16 v[26:29], v[154:157], v[162:165], v[26:29]
	v_mfma_f32_16x16x32_bf16 v[22:25], v[146:149], v[170:173], v[22:25]
	v_mfma_f32_16x16x32_bf16 v[18:21], v[154:157], v[170:173], v[18:21]
	v_mfma_f32_16x16x32_bf16 v[14:17], v[146:149], v[178:181], v[14:17]
	v_mfma_f32_16x16x32_bf16 v[10:13], v[154:157], v[178:181], v[10:13]
	v_mfma_f32_16x16x32_bf16 v[6:9], v[146:149], v[186:189], v[6:9]
	v_mfma_f32_16x16x32_bf16 v[2:5], v[154:157], v[186:189], v[2:5]
	v_mfma_f32_16x16x32_bf16 v[30:33], v[150:153], v[166:169], v[30:33]
	v_mfma_f32_16x16x32_bf16 v[26:29], v[158:161], v[166:169], v[26:29]
	v_mfma_f32_16x16x32_bf16 v[22:25], v[150:153], v[174:177], v[22:25]
	v_mfma_f32_16x16x32_bf16 v[18:21], v[158:161], v[174:177], v[18:21]
	v_mfma_f32_16x16x32_bf16 v[14:17], v[150:153], v[182:185], v[14:17]
	v_mfma_f32_16x16x32_bf16 v[10:13], v[158:161], v[182:185], v[10:13]
	v_mfma_f32_16x16x32_bf16 v[6:9], v[150:153], v[190:193], v[6:9]
	v_mfma_f32_16x16x32_bf16 v[2:5], v[158:161], v[190:193], v[2:5]
	s_barrier
	s_add_u32 s11, s11, 0x100
	s_addc_u32 s53, s53, 0
	s_add_u32 s24, s24, 0x100
	s_addc_u32 s25, s25, 0
	s_cmp_ge_u32 s61, s5
	s_mov_b32 s26, s61
	s_cbranch_scc0 .LBB0_1128
	s_and_b64 vcc, s[50:51], s[40:41]
	s_cbranch_vccz .LBB0_1131
	s_barrier

; #define PG8_BAR __builtin_amdgcn_s_barrier()
; template <class Epi, class Sched, bool ALIGN_EPI, bool SP2>
; __device__ __forceinline__ void gemm_phase(LAS unsigned char* lds, const int tid, const Gemm g, const Sched& S, const Epi& E) {
;     ...
;         cur = nxt; cA = nA; cB = nB; ++ui;
;         if constexpr (ALIGN_EPI) { if (wr == 1) PG8_BAR; }
.LBB0_1166:
	s_and_b64 vcc, exec, s[38:39]
	s_cbranch_vccnz .LBB0_1119
	s_branch .LBB0_1119
